# conversion loops: alternate matrices start from the opposite end of the wave range so per-wave item counts balance across matrices
# speedup vs baseline: 1.0095x; 1.0072x over previous
; #define LAS __attribute__((address_space(3)))
; __device__ __forceinline__ void conv_matrix(const float* W, int K, int N, const float* gain, bf16_t* WT, int Kd, int mode, int row_off, LAS float* scr, int lane, int gw, int NGW) {
;     const int nblk = N / 32, items = nblk * (K / 64);
;     for (int it = gw; it < items; it += NGW) {
;         const int kb = it / nblk, nb = it % nblk, k0 = 64 * kb, n0 = 32 * nb;
;         float wv[32];
; #pragma unroll
;         for (int i = 0; i < 32; ++i) wv[i] = W[(size_t)(k0 + 2 * i + (lane >> 5)) * N + n0 + (lane & 31)];
.LBB0_85:
	v_lshlrev_b32_e32 v10, 2, v10
	v_mov_b32_e32 v11, v0
	v_lshl_add_u64 v[2:3], v[2:3], 0, v[10:11]
	s_sub_i32 s27, s8, s4
	s_add_i32 s27, s27, -1
	s_lshl_b32 s25, s27, 5
	s_lshl_b32 s24, s27, 6
	s_cmp_lg_u32 s58, 0
	s_cbranch_scc1 .LBB0_89
	s_branch .LBB0_87

; #define LAS __attribute__((address_space(3)))
; __device__ __forceinline__ void conv_matrix(const float* W, int K, int N, const float* gain, bf16_t* WT, int Kd, int mode, int row_off, LAS float* scr, int lane, int gw, int NGW) {
;     const int nblk = N / 32, items = nblk * (K / 64);
;     for (int it = gw; it < items; it += NGW) {
;         const int kb = it / nblk, nb = it % nblk, k0 = 64 * kb, n0 = 32 * nb;
;         float wv[32];
; #pragma unroll
;         for (int i = 0; i < 32; ++i) wv[i] = W[(size_t)(k0 + 2 * i + (lane >> 5)) * N + n0 + (lane & 31)];
.LBB0_95:
	v_mov_b32_e32 v11, v0
	v_lshl_add_u64 v[2:3], v[2:3], 0, v[10:11]
	s_sub_i32 s27, s8, s4
	s_add_i32 s27, s27, -1
	s_lshl_b32 s25, s27, 5
	s_lshl_b32 s22, s27, 6
	s_cmp_lg_u32 s58, 7
	s_cbranch_scc1 .LBB0_99
	s_branch .LBB0_97

; #define LAS __attribute__((address_space(3)))
; __device__ __forceinline__ void conv_matrix(const float* W, int K, int N, const float* gain, bf16_t* WT, int Kd, int mode, int row_off, LAS float* scr, int lane, int gw, int NGW) {
;     const int nblk = N / 32, items = nblk * (K / 64);
;     for (int it = gw; it < items; it += NGW) {
;         const int kb = it / nblk, nb = it % nblk, k0 = 64 * kb, n0 = 32 * nb;
;         float wv[32];
; #pragma unroll
;         for (int i = 0; i < 32; ++i) wv[i] = W[(size_t)(k0 + 2 * i + (lane >> 5)) * N + n0 + (lane & 31)];
.Lskip_b3:
.LBB0_101:
	s_cmp_lg_u32 s58, 0
	s_cbranch_scc1 .LBB0_106
	s_cmpk_gt_i32 s4, 0x131f
	s_cbranch_scc1 .LBB0_106
	v_readlane_b32 s9, v254, 8
	v_lshlrev_b32_e32 v6, 2, v54
	v_and_b32_e32 v6, 0x7c, v6
	s_waitcnt lgkmcnt(0)
	v_mov_b32_e32 v2, s9
	v_readlane_b32 s9, v254, 9
	v_mov_b32_e32 v7, v0
	v_add_u32_e32 v8, s5, v6
	v_mov_b32_e32 v4, s9
	ds_read_b64 v[2:3], v2
	ds_read_b64 v[4:5], v4
	v_lshrrev_b32_e32 v44, 3, v1
	v_lshrrev_b32_e32 v35, 5, v1
	v_lshlrev_b32_e32 v10, 2, v44
	s_mov_b64 s[16:17], 0x9900000
	s_waitcnt lgkmcnt(0)
	v_lshl_add_u64 v[4:5], v[4:5], 0, v[6:7]
	v_lshlrev_b32_e32 v6, 3, v1
	v_and_b32_e32 v6, 56, v6
	v_mul_u32_u24_e32 v9, 0x84, v6
	v_lshlrev_b32_e32 v6, 1, v6
	v_lshl_add_u64 v[6:7], s[0:1], 0, v[6:7]
	v_add3_u32 v45, s5, v9, v10
	v_mul_u32_u24_e32 v9, 0x84, v35
	v_cmp_ne_u64_e64 s[38:39], 0, v[2:3]
	v_lshl_add_u64 v[6:7], v[6:7], 0, s[16:17]
	s_lshl_b32 s9, s4, 5
	s_lshl_b32 s12, s8, 5
	v_add_u32_e32 v46, v8, v9
	s_sub_i32 s22, s8, s4
	s_add_i32 s22, s22, -1
	s_lshl_b32 s9, s22, 5
	s_branch .LBB0_104
